# phase-0 latency: mod_item silu staging issues all 18 loads before computing (was 18 dependent load-compute trips); filter W1 staging issues its 5 loads up front (was 5 dependent trips)
# speedup vs baseline: 1.0166x; 1.0012x over previous
.LBB0_106:
	s_mov_b64 s[98:99], exec
	s_movk_i32 s12, 0x63f
	s_mov_b64 s[10:11], 0x1000
	v_lshl_add_u64 v[82:83], v[46:47], 0, s[10:11]
	v_lshl_add_u64 v[84:85], v[82:83], 0, s[10:11]
	global_load_dword v49, v[46:47], off
	v_add_u32_e32 v87, 0x200, v70
	v_cmp_ge_u32_e32 vcc, s12, v87
	s_and_b64 exec, s[98:99], vcc
	global_load_dword v80, v[46:47], off offset:2048
	v_add_u32_e32 v87, 0x400, v70
	v_cmp_ge_u32_e32 vcc, s12, v87
	s_and_b64 exec, s[98:99], vcc
	global_load_dword v81, v[82:83], off
	v_add_u32_e32 v87, 0x600, v70
	v_cmp_ge_u32_e32 vcc, s12, v87
	s_and_b64 exec, s[98:99], vcc
	global_load_dword v86, v[82:83], off offset:2048
	v_add_u32_e32 v87, 0x800, v70
	v_cmp_ge_u32_e32 vcc, s12, v87
	s_and_b64 exec, s[98:99], vcc
	global_load_dword v88, v[84:85], off
	s_mov_b64 exec, s[98:99]
	s_waitcnt vmcnt(4)
	ds_write_b32 v4, v49
	v_add_u32_e32 v87, 0x200, v70
	v_cmp_ge_u32_e32 vcc, s12, v87
	s_and_b64 exec, s[98:99], vcc
	s_waitcnt vmcnt(3)
	ds_write_b32 v4, v80 offset:2048
	v_add_u32_e32 v87, 0x400, v70
	v_cmp_ge_u32_e32 vcc, s12, v87
	s_and_b64 exec, s[98:99], vcc
	s_waitcnt vmcnt(2)
	ds_write_b32 v4, v81 offset:4096
	v_add_u32_e32 v87, 0x600, v70
	v_cmp_ge_u32_e32 vcc, s12, v87
	s_and_b64 exec, s[98:99], vcc
	s_waitcnt vmcnt(1)
	ds_write_b32 v4, v86 offset:6144
	v_add_u32_e32 v87, 0x800, v70
	v_cmp_ge_u32_e32 vcc, s12, v87
	s_and_b64 exec, s[98:99], vcc
	s_waitcnt vmcnt(0)
	ds_write_b32 v4, v88 offset:8192
	s_mov_b64 exec, s[98:99]
	s_mov_b64 s[0:1], 0
	s_or_b64 exec, exec, s[0:1]
	global_load_dword v4, v[16:17], off
	global_load_dword v46, v[18:19], off
	global_load_dword v47, v[16:17], off offset:2048
	global_load_dword v48, v[18:19], off offset:2048
	global_load_dword v49, v[20:21], off
	global_load_dword v80, v[22:23], off
	global_load_dword v81, v[24:25], off
	global_load_dword v82, v[26:27], off
	global_load_dword v83, v[28:29], off
	global_load_dword v84, v[30:31], off
	global_load_dword v85, v[32:33], off
	global_load_dword v86, v[34:35], off
	global_load_dword v87, v[36:37], off
	global_load_dword v88, v[38:39], off
	s_waitcnt vmcnt(13)
	ds_write_b32 v3, v4
	s_waitcnt vmcnt(12)
	ds_write_b32 v55, v46
	s_waitcnt vmcnt(11)
	ds_write_b32 v56, v47
	s_waitcnt vmcnt(10)
	ds_write_b32 v57, v48
	s_waitcnt vmcnt(9)
	ds_write_b32 v58, v49
	s_waitcnt vmcnt(8)
	ds_write_b32 v59, v80
	s_waitcnt vmcnt(7)
	ds_write_b32 v60, v81
	s_waitcnt vmcnt(6)
	ds_write_b32 v61, v82
	s_waitcnt vmcnt(5)
	ds_write_b32 v62, v83
	s_waitcnt vmcnt(4)
	ds_write_b32 v63, v84
	s_waitcnt vmcnt(3)
	ds_write_b32 v64, v85
	s_waitcnt vmcnt(2)
	ds_write_b32 v65, v86
	s_waitcnt vmcnt(1)
	ds_write_b32 v66, v87
	s_waitcnt vmcnt(0)
	ds_write_b32 v67, v88
	s_and_saveexec_b64 s[0:1], s[8:9]
	s_cbranch_execz .LBB0_109
	global_load_dword v4, v[40:41], off
	global_load_dword v46, v[42:43], off
	s_waitcnt vmcnt(1)
	ds_write_b32 v68, v4
	s_waitcnt vmcnt(0)
	ds_write_b32 v69, v46

.LBB0_153:
	s_mov_b64 s[6:7], 0x1000
	global_load_dword v200, v[2:3], off
	global_load_dword v201, v[2:3], off offset:2048
	v_lshl_add_u64 v[2:3], v[2:3], 0, s[6:7]
	global_load_dword v202, v[2:3], off
	global_load_dword v203, v[2:3], off offset:2048
	v_lshl_add_u64 v[2:3], v[2:3], 0, s[6:7]
	global_load_dword v204, v[2:3], off
	global_load_dword v205, v[2:3], off offset:2048
	v_lshl_add_u64 v[2:3], v[2:3], 0, s[6:7]
	global_load_dword v206, v[2:3], off
	global_load_dword v207, v[2:3], off offset:2048
	v_lshl_add_u64 v[2:3], v[2:3], 0, s[6:7]
	global_load_dword v208, v[2:3], off
	global_load_dword v209, v[2:3], off offset:2048
	v_lshl_add_u64 v[2:3], v[2:3], 0, s[6:7]
	global_load_dword v210, v[2:3], off
	global_load_dword v211, v[2:3], off offset:2048
	v_lshl_add_u64 v[2:3], v[2:3], 0, s[6:7]
	global_load_dword v212, v[2:3], off
	global_load_dword v213, v[2:3], off offset:2048
	v_lshl_add_u64 v[2:3], v[2:3], 0, s[6:7]
	global_load_dword v214, v[2:3], off
	global_load_dword v215, v[2:3], off offset:2048
	s_mov_b64 s[6:7], 0x8000
	v_lshl_add_u64 v[0:1], v[0:1], 0, s[6:7]
	global_load_dword v216, v[0:1], off
	global_load_dword v217, v[0:1], off offset:2048
	s_waitcnt vmcnt(17)
	v_mul_f32_e32 v7, 0xbfb8aa3b, v200
	v_exp_f32_e32 v7, v7
	s_nop 0
	v_add_f32_e32 v7, 1.0, v7
	v_div_scale_f32 v8, s[6:7], v7, v7, v200
	v_rcp_f32_e32 v9, v8
	v_div_scale_f32 v10, vcc, v200, v7, v200
	v_fma_f32 v11, -v8, v9, 1.0
	v_fmac_f32_e32 v9, v11, v9
	v_mul_f32_e32 v11, v10, v9
	v_fma_f32 v12, -v8, v11, v10
	v_fmac_f32_e32 v11, v12, v9
	v_fma_f32 v8, -v8, v11, v10
	v_div_fmas_f32 v8, v8, v9, v11
	v_div_fixup_f32 v6, v8, v7, v200
	ds_write_b32 v4, v6
	s_waitcnt vmcnt(16)
	v_mul_f32_e32 v7, 0xbfb8aa3b, v201
	v_exp_f32_e32 v7, v7
	s_nop 0
	v_add_f32_e32 v7, 1.0, v7
	v_div_scale_f32 v8, s[6:7], v7, v7, v201
	v_rcp_f32_e32 v9, v8
	v_div_scale_f32 v10, vcc, v201, v7, v201
	v_fma_f32 v11, -v8, v9, 1.0
	v_fmac_f32_e32 v9, v11, v9
	v_mul_f32_e32 v11, v10, v9
	v_fma_f32 v12, -v8, v11, v10
	v_fmac_f32_e32 v11, v12, v9
	v_fma_f32 v8, -v8, v11, v10
	v_div_fmas_f32 v8, v8, v9, v11
	v_div_fixup_f32 v6, v8, v7, v201
	ds_write_b32 v4, v6 offset:2048
	s_waitcnt vmcnt(15)
	v_mul_f32_e32 v7, 0xbfb8aa3b, v202
	v_exp_f32_e32 v7, v7
	s_nop 0
	v_add_f32_e32 v7, 1.0, v7
	v_div_scale_f32 v8, s[6:7], v7, v7, v202
	v_rcp_f32_e32 v9, v8
	v_div_scale_f32 v10, vcc, v202, v7, v202
	v_fma_f32 v11, -v8, v9, 1.0
	v_fmac_f32_e32 v9, v11, v9
	v_mul_f32_e32 v11, v10, v9
	v_fma_f32 v12, -v8, v11, v10
	v_fmac_f32_e32 v11, v12, v9
	v_fma_f32 v8, -v8, v11, v10
	v_div_fmas_f32 v8, v8, v9, v11
	v_div_fixup_f32 v6, v8, v7, v202
	ds_write_b32 v4, v6 offset:4096
	s_waitcnt vmcnt(14)
	v_mul_f32_e32 v7, 0xbfb8aa3b, v203
	v_exp_f32_e32 v7, v7
	s_nop 0
	v_add_f32_e32 v7, 1.0, v7
	v_div_scale_f32 v8, s[6:7], v7, v7, v203
	v_rcp_f32_e32 v9, v8
	v_div_scale_f32 v10, vcc, v203, v7, v203
	v_fma_f32 v11, -v8, v9, 1.0
	v_fmac_f32_e32 v9, v11, v9
	v_mul_f32_e32 v11, v10, v9
	v_fma_f32 v12, -v8, v11, v10
	v_fmac_f32_e32 v11, v12, v9
	v_fma_f32 v8, -v8, v11, v10
	v_div_fmas_f32 v8, v8, v9, v11
	v_div_fixup_f32 v6, v8, v7, v203
	ds_write_b32 v4, v6 offset:6144
	s_waitcnt vmcnt(13)
	v_mul_f32_e32 v7, 0xbfb8aa3b, v204
	v_exp_f32_e32 v7, v7
	s_nop 0
	v_add_f32_e32 v7, 1.0, v7
	v_div_scale_f32 v8, s[6:7], v7, v7, v204
	v_rcp_f32_e32 v9, v8
	v_div_scale_f32 v10, vcc, v204, v7, v204
	v_fma_f32 v11, -v8, v9, 1.0
	v_fmac_f32_e32 v9, v11, v9
	v_mul_f32_e32 v11, v10, v9
	v_fma_f32 v12, -v8, v11, v10
	v_fmac_f32_e32 v11, v12, v9
	v_fma_f32 v8, -v8, v11, v10
	v_div_fmas_f32 v8, v8, v9, v11
	v_div_fixup_f32 v6, v8, v7, v204
	ds_write_b32 v4, v6 offset:8192
	s_waitcnt vmcnt(12)
	v_mul_f32_e32 v7, 0xbfb8aa3b, v205
	v_exp_f32_e32 v7, v7
	s_nop 0
	v_add_f32_e32 v7, 1.0, v7
	v_div_scale_f32 v8, s[6:7], v7, v7, v205
	v_rcp_f32_e32 v9, v8
	v_div_scale_f32 v10, vcc, v205, v7, v205
	v_fma_f32 v11, -v8, v9, 1.0
	v_fmac_f32_e32 v9, v11, v9
	v_mul_f32_e32 v11, v10, v9
	v_fma_f32 v12, -v8, v11, v10
	v_fmac_f32_e32 v11, v12, v9
	v_fma_f32 v8, -v8, v11, v10
	v_div_fmas_f32 v8, v8, v9, v11
	v_div_fixup_f32 v6, v8, v7, v205
	ds_write_b32 v4, v6 offset:10240
	s_waitcnt vmcnt(11)
	v_mul_f32_e32 v7, 0xbfb8aa3b, v206
	v_exp_f32_e32 v7, v7
	s_nop 0
	v_add_f32_e32 v7, 1.0, v7
	v_div_scale_f32 v8, s[6:7], v7, v7, v206
	v_rcp_f32_e32 v9, v8
	v_div_scale_f32 v10, vcc, v206, v7, v206
	v_fma_f32 v11, -v8, v9, 1.0
	v_fmac_f32_e32 v9, v11, v9
	v_mul_f32_e32 v11, v10, v9
	v_fma_f32 v12, -v8, v11, v10
	v_fmac_f32_e32 v11, v12, v9
	v_fma_f32 v8, -v8, v11, v10
	v_div_fmas_f32 v8, v8, v9, v11
	v_div_fixup_f32 v6, v8, v7, v206
	ds_write_b32 v4, v6 offset:12288
	s_waitcnt vmcnt(10)
	v_mul_f32_e32 v7, 0xbfb8aa3b, v207
	v_exp_f32_e32 v7, v7
	s_nop 0
	v_add_f32_e32 v7, 1.0, v7
	v_div_scale_f32 v8, s[6:7], v7, v7, v207
	v_rcp_f32_e32 v9, v8
	v_div_scale_f32 v10, vcc, v207, v7, v207
	v_fma_f32 v11, -v8, v9, 1.0
	v_fmac_f32_e32 v9, v11, v9
	v_mul_f32_e32 v11, v10, v9
	v_fma_f32 v12, -v8, v11, v10
	v_fmac_f32_e32 v11, v12, v9
	v_fma_f32 v8, -v8, v11, v10
	v_div_fmas_f32 v8, v8, v9, v11
	v_div_fixup_f32 v6, v8, v7, v207
	ds_write_b32 v4, v6 offset:14336
	s_waitcnt vmcnt(9)
	v_mul_f32_e32 v7, 0xbfb8aa3b, v208
	v_exp_f32_e32 v7, v7
	s_nop 0
	v_add_f32_e32 v7, 1.0, v7
	v_div_scale_f32 v8, s[6:7], v7, v7, v208
	v_rcp_f32_e32 v9, v8
	v_div_scale_f32 v10, vcc, v208, v7, v208
	v_fma_f32 v11, -v8, v9, 1.0
	v_fmac_f32_e32 v9, v11, v9
	v_mul_f32_e32 v11, v10, v9
	v_fma_f32 v12, -v8, v11, v10
	v_fmac_f32_e32 v11, v12, v9
	v_fma_f32 v8, -v8, v11, v10
	v_div_fmas_f32 v8, v8, v9, v11
	v_div_fixup_f32 v6, v8, v7, v208
	ds_write_b32 v4, v6 offset:16384
	s_waitcnt vmcnt(8)
	v_mul_f32_e32 v7, 0xbfb8aa3b, v209
	v_exp_f32_e32 v7, v7
	s_nop 0
	v_add_f32_e32 v7, 1.0, v7
	v_div_scale_f32 v8, s[6:7], v7, v7, v209
	v_rcp_f32_e32 v9, v8
	v_div_scale_f32 v10, vcc, v209, v7, v209
	v_fma_f32 v11, -v8, v9, 1.0
	v_fmac_f32_e32 v9, v11, v9
	v_mul_f32_e32 v11, v10, v9
	v_fma_f32 v12, -v8, v11, v10
	v_fmac_f32_e32 v11, v12, v9
	v_fma_f32 v8, -v8, v11, v10
	v_div_fmas_f32 v8, v8, v9, v11
	v_div_fixup_f32 v6, v8, v7, v209
	ds_write_b32 v4, v6 offset:18432
	s_waitcnt vmcnt(7)
	v_mul_f32_e32 v7, 0xbfb8aa3b, v210
	v_exp_f32_e32 v7, v7
	s_nop 0
	v_add_f32_e32 v7, 1.0, v7
	v_div_scale_f32 v8, s[6:7], v7, v7, v210
	v_rcp_f32_e32 v9, v8
	v_div_scale_f32 v10, vcc, v210, v7, v210
	v_fma_f32 v11, -v8, v9, 1.0
	v_fmac_f32_e32 v9, v11, v9
	v_mul_f32_e32 v11, v10, v9
	v_fma_f32 v12, -v8, v11, v10
	v_fmac_f32_e32 v11, v12, v9
	v_fma_f32 v8, -v8, v11, v10
	v_div_fmas_f32 v8, v8, v9, v11
	v_div_fixup_f32 v6, v8, v7, v210
	ds_write_b32 v4, v6 offset:20480
	s_waitcnt vmcnt(6)
	v_mul_f32_e32 v7, 0xbfb8aa3b, v211
	v_exp_f32_e32 v7, v7
	s_nop 0
	v_add_f32_e32 v7, 1.0, v7
	v_div_scale_f32 v8, s[6:7], v7, v7, v211
	v_rcp_f32_e32 v9, v8
	v_div_scale_f32 v10, vcc, v211, v7, v211
	v_fma_f32 v11, -v8, v9, 1.0
	v_fmac_f32_e32 v9, v11, v9
	v_mul_f32_e32 v11, v10, v9
	v_fma_f32 v12, -v8, v11, v10
	v_fmac_f32_e32 v11, v12, v9
	v_fma_f32 v8, -v8, v11, v10
	v_div_fmas_f32 v8, v8, v9, v11
	v_div_fixup_f32 v6, v8, v7, v211
	ds_write_b32 v4, v6 offset:22528
	s_waitcnt vmcnt(5)
	v_mul_f32_e32 v7, 0xbfb8aa3b, v212
	v_exp_f32_e32 v7, v7
	s_nop 0
	v_add_f32_e32 v7, 1.0, v7
	v_div_scale_f32 v8, s[6:7], v7, v7, v212
	v_rcp_f32_e32 v9, v8
	v_div_scale_f32 v10, vcc, v212, v7, v212
	v_fma_f32 v11, -v8, v9, 1.0
	v_fmac_f32_e32 v9, v11, v9
	v_mul_f32_e32 v11, v10, v9
	v_fma_f32 v12, -v8, v11, v10
	v_fmac_f32_e32 v11, v12, v9
	v_fma_f32 v8, -v8, v11, v10
	v_div_fmas_f32 v8, v8, v9, v11
	v_div_fixup_f32 v6, v8, v7, v212
	ds_write_b32 v4, v6 offset:24576
	s_waitcnt vmcnt(4)
	v_mul_f32_e32 v7, 0xbfb8aa3b, v213
	v_exp_f32_e32 v7, v7
	s_nop 0
	v_add_f32_e32 v7, 1.0, v7
	v_div_scale_f32 v8, s[6:7], v7, v7, v213
	v_rcp_f32_e32 v9, v8
	v_div_scale_f32 v10, vcc, v213, v7, v213
	v_fma_f32 v11, -v8, v9, 1.0
	v_fmac_f32_e32 v9, v11, v9
	v_mul_f32_e32 v11, v10, v9
	v_fma_f32 v12, -v8, v11, v10
	v_fmac_f32_e32 v11, v12, v9
	v_fma_f32 v8, -v8, v11, v10
	v_div_fmas_f32 v8, v8, v9, v11
	v_div_fixup_f32 v6, v8, v7, v213
	ds_write_b32 v4, v6 offset:26624
	s_waitcnt vmcnt(3)
	v_mul_f32_e32 v7, 0xbfb8aa3b, v214
	v_exp_f32_e32 v7, v7
	s_nop 0
	v_add_f32_e32 v7, 1.0, v7
	v_div_scale_f32 v8, s[6:7], v7, v7, v214
	v_rcp_f32_e32 v9, v8
	v_div_scale_f32 v10, vcc, v214, v7, v214
	v_fma_f32 v11, -v8, v9, 1.0
	v_fmac_f32_e32 v9, v11, v9
	v_mul_f32_e32 v11, v10, v9
	v_fma_f32 v12, -v8, v11, v10
	v_fmac_f32_e32 v11, v12, v9
	v_fma_f32 v8, -v8, v11, v10
	v_div_fmas_f32 v8, v8, v9, v11
	v_div_fixup_f32 v6, v8, v7, v214
	ds_write_b32 v4, v6 offset:28672
	s_waitcnt vmcnt(2)
	v_mul_f32_e32 v7, 0xbfb8aa3b, v215
	v_exp_f32_e32 v7, v7
	s_nop 0
	v_add_f32_e32 v7, 1.0, v7
	v_div_scale_f32 v8, s[6:7], v7, v7, v215
	v_rcp_f32_e32 v9, v8
	v_div_scale_f32 v10, vcc, v215, v7, v215
	v_fma_f32 v11, -v8, v9, 1.0
	v_fmac_f32_e32 v9, v11, v9
	v_mul_f32_e32 v11, v10, v9
	v_fma_f32 v12, -v8, v11, v10
	v_fmac_f32_e32 v11, v12, v9
	v_fma_f32 v8, -v8, v11, v10
	v_div_fmas_f32 v8, v8, v9, v11
	v_div_fixup_f32 v6, v8, v7, v215
	ds_write_b32 v4, v6 offset:30720
	s_waitcnt vmcnt(1)
	v_mul_f32_e32 v7, 0xbfb8aa3b, v216
	v_exp_f32_e32 v7, v7
	s_nop 0
	v_add_f32_e32 v7, 1.0, v7
	v_div_scale_f32 v8, s[6:7], v7, v7, v216
	v_rcp_f32_e32 v9, v8
	v_div_scale_f32 v10, vcc, v216, v7, v216
	v_fma_f32 v11, -v8, v9, 1.0
	v_fmac_f32_e32 v9, v11, v9
	v_mul_f32_e32 v11, v10, v9
	v_fma_f32 v12, -v8, v11, v10
	v_fmac_f32_e32 v11, v12, v9
	v_fma_f32 v8, -v8, v11, v10
	v_div_fmas_f32 v8, v8, v9, v11
	v_div_fixup_f32 v6, v8, v7, v216
	ds_write_b32 v4, v6 offset:32768
	s_waitcnt vmcnt(0)
	v_mul_f32_e32 v7, 0xbfb8aa3b, v217
	v_exp_f32_e32 v7, v7
	s_nop 0
	v_add_f32_e32 v7, 1.0, v7
	v_div_scale_f32 v8, s[6:7], v7, v7, v217
	v_rcp_f32_e32 v9, v8
	v_div_scale_f32 v10, vcc, v217, v7, v217
	v_fma_f32 v11, -v8, v9, 1.0
	v_fmac_f32_e32 v9, v11, v9
	v_mul_f32_e32 v11, v10, v9
	v_fma_f32 v12, -v8, v11, v10
	v_fmac_f32_e32 v11, v12, v9
	v_fma_f32 v8, -v8, v11, v10
	v_div_fmas_f32 v8, v8, v9, v11
	v_div_fixup_f32 v6, v8, v7, v217
	ds_write_b32 v4, v6 offset:34816
	s_or_b64 exec, exec, s[0:1]
	v_and_b32_e32 v161, 63, v160
	s_lshl_b32 s4, s20, 6
	v_or_b32_e32 v144, s4, v161
	v_mov_b32_e32 v145, 0
	v_lshrrev_b32_e32 v2, 6, v160
	v_lshlrev_b64 v[0:1], 2, v[144:145]
	s_mov_b32 s0, 0x300000
	v_readlane_b32 s36, v240, 8
	v_mad_u64_u32 v[0:1], s[0:1], v2, s0, v[0:1]
	v_readlane_b32 s44, v240, 16
	v_readlane_b32 s45, v240, 17
	v_lshrrev_b32_e32 v169, 6, v160
	s_mov_b64 s[0:1], 0x5a000
	v_lshl_add_u64 v[0:1], s[44:45], 0, v[0:1]
	v_lshl_add_u64 v[146:147], v[0:1], 0, s[0:1]
	v_lshl_add_u32 v184, v169, 9, 0
	s_mov_b32 s5, -4
	s_mov_b32 s6, 0xfffbe000
	s_mov_b32 s7, 0xfffc4000
	s_mov_b32 s8, 0xfffca000
	s_mov_b32 s9, 0xfffd0000
	s_mov_b32 s10, 0xfffd6000
	s_mov_b32 s11, 0xfffdc000
	s_mov_b32 s12, 0xfffe2000
	s_mov_b32 s13, 0xfffe8000
	s_mov_b32 s14, 0xfffee000
	s_mov_b32 s15, 0xffff4000
	s_movk_i32 s24, 0xa000
	s_mov_b64 s[2:3], 0x60000
	v_mov_b32_e32 v148, v145
	v_mov_b32_e32 v149, v145
	v_mov_b32_e32 v150, v145
	v_mov_b32_e32 v151, v145
	v_mov_b32_e32 v152, v145
	v_mov_b32_e32 v153, v145
	v_mov_b32_e32 v154, v145
	v_mov_b32_e32 v155, v145
	v_mov_b32_e32 v185, v145
	s_waitcnt lgkmcnt(0)
	s_barrier
	v_readlane_b32 s37, v240, 9
	v_readlane_b32 s38, v240, 10
	v_readlane_b32 s39, v240, 11
	v_readlane_b32 s40, v240, 12
	v_readlane_b32 s41, v240, 13
	v_readlane_b32 s42, v240, 14
	v_readlane_b32 s43, v240, 15
	v_readlane_b32 s46, v240, 18
	v_readlane_b32 s47, v240, 19
	v_readlane_b32 s48, v240, 20
	v_readlane_b32 s49, v240, 21
	v_readlane_b32 s50, v240, 22
	v_readlane_b32 s51, v240, 23
